# merged X+S scan stage: waves 4-7 fold COMMIT arithmetic/ISSUE into LDS+MFMA latency; PREP quarters on waves 0-3 at s_setprio 2
# baseline (speedup 1.0000x reference)
.Lsx0_c:
	s_or_b64 exec, exec, s[2:3]
	v_mov_b32_e32 v22, 0
	v_mov_b32_e32 v23, 0
	v_mov_b32_e32 v24, 0
	v_mov_b32_e32 v25, 0
	s_and_saveexec_b64 s[2:3], s[56:57]
	s_cbranch_execz .LBB0_403
	ds_read_b128 v[48:51], v174
	ds_read_b128 v[60:63], v192 offset:49152
	ds_read_b128 v[52:55], v174 offset:64
	ds_read_b128 v[64:67], v192 offset:49216
	ds_read_b128 v[56:59], v175
	ds_read_b128 v[68:71], v199
	ds_read_b128 v[72:75], v192 offset:58368
	ds_read_b128 v[76:79], v192 offset:58432
	ds_read_b128 v[80:83], v151
	ds_read_b128 v[84:87], v151 offset:16
	ds_read_b128 v[88:91], v151 offset:32
	ds_read_b128 v[92:95], v151 offset:48
	s_cmp_gt_u32 s36, 62
	s_cbranch_scc1 .Lcp0
	s_waitcnt vmcnt(4)
	v_lshlrev_b32_e32 v136, 16, v1
	v_and_b32_e32 v137, 0xffff0000, v1
	v_pk_mul_f32 v[124:125], v[102:103], v[136:137]
	s_waitcnt vmcnt(1)
	v_lshlrev_b32_e32 v126, 16, v3
	s_waitcnt vmcnt(0)
	v_pk_mul_f32 v[124:125], v[108:109], v[124:125] op_sel_hi:[0,1]
	v_and_b32_e32 v127, 0xffff0000, v3
	v_lshlrev_b32_e32 v130, 16, v4
	v_and_b32_e32 v131, 0xffff0000, v4
	v_pk_add_f32 v[128:129], v[130:131], -1.0 op_sel_hi:[1,0]
	v_pk_mul_f32 v[130:131], v[130:131], v[124:125] neg_lo:[0,1] neg_hi:[0,1]
	v_pk_fma_f32 v[128:129], v[104:105], v[128:129], 1.0 op_sel_hi:[1,1,0]
	s_nop 0
	v_pk_mul_f32 v[128:129], v[128:129], v[136:137]
	v_lshlrev_b32_e32 v132, 16, v0
	v_and_b32_e32 v133, 0xffff0000, v0
	v_lshlrev_b32_e32 v134, 16, v2
	v_and_b32_e32 v135, 0xffff0000, v2
.Lcp0:
	s_waitcnt lgkmcnt(10)
	v_mfma_f32_16x16x32_bf16 v[30:33], v[48:51], v[60:63], 0
	s_waitcnt lgkmcnt(8)
	v_mfma_f32_16x16x32_bf16 v[30:33], v[52:55], v[64:67], v[30:33]
	s_waitcnt lgkmcnt(6)
	v_mfma_f32_16x16x32_bf16 v[30:33], v[56:59], v[68:71], v[30:33]
	s_waitcnt lgkmcnt(5)
	v_mfma_f32_16x16x32_bf16 v[22:25], v[48:51], v[72:75], 0
	s_waitcnt lgkmcnt(4)
	v_mfma_f32_16x16x32_bf16 v[22:25], v[52:55], v[76:79], v[22:25]
	s_cmp_eq_u32 s36, 0
	s_cbranch_scc1 .Lis0b
	s_cmp_gt_u32 s36, 62
	s_cbranch_scc1 .Lis0b
	s_add_i32 s24, s19, 0xffffffc0
	s_add_i32 s25, s21, 0x30
	s_and_b64 s[98:99], s[12:13], exec
	s_cselect_b32 s24, s25, s24
	v_lshl_add_u32 v194, s24, 6, v183
	v_lshlrev_b32_e32 v112, 1, v194
	global_load_dword v5, v112, s[44:45]
	global_load_dword v6, v112, s[42:43]
	global_load_dword v7, v112, s[0:1]
	global_load_dword v8, v112, s[34:35]
	global_load_dword v9, v112, s[76:77]
	v_add_u32_e32 v194, s24, v184
	v_lshlrev_b32_e32 v114, 2, v194
	global_load_dword v110, v114, s[40:41]
.Lis0b:
	s_cmp_lg_u32 s21, 0
	s_cbranch_scc0 .Lsx0_d
	v_cvt_pk_bf16_f32 v240, v236, v237
	global_store_dword v[238:239], v240, off

.LBB0_403:
	s_or_b64 exec, exec, s[2:3]
	s_waitcnt lgkmcnt(0)
.LBB0_405:
	v_lshrrev_b32_e32 v122, 6, v198
	s_nop 0
	v_readfirstlane_b32 s98, v122
	s_nop 3
	s_cmp_eq_u32 s98, 0
	s_cbranch_scc1 .Lpq0_q0
	s_cmp_eq_u32 s98, 1
	s_cbranch_scc1 .Lpq0_q1
	s_cmp_eq_u32 s98, 2
	s_cbranch_scc1 .Lpq0_q2
	s_cmp_eq_u32 s98, 3
	s_cbranch_scc1 .Lpq0_q3
	s_branch .Lpq0_end
.Lpq0_q0:
	s_setprio 2
	ds_read2st64_b32 v[40:41], v143 offset0:96 offset1:97
	ds_read2st64_b32 v[42:43], v143 offset0:98 offset1:99
	ds_read2st64_b32 v[44:45], v143 offset0:100 offset1:101
	ds_read2st64_b32 v[46:47], v143 offset0:102 offset1:103
	ds_read2st64_b32 v[48:49], v143 offset0:104 offset1:105
	ds_read2st64_b32 v[50:51], v143 offset0:106 offset1:107
	ds_read2st64_b32 v[52:53], v143 offset0:108 offset1:109
	ds_read2st64_b32 v[54:55], v143 offset0:110 offset1:111
	ds_read2st64_b32 v[56:57], v143 offset0:112 offset1:113
	ds_read2st64_b32 v[58:59], v143 offset0:114 offset1:115
	ds_read2st64_b32 v[60:61], v143 offset0:116 offset1:117
	ds_read2st64_b32 v[62:63], v143 offset0:118 offset1:119
	v_lshrrev_b32_e32 v122, 1, v143
	v_mov_b32_e32 v69, 0
	s_waitcnt lgkmcnt(11)
	v_add_f32_e32 v65, v69, v41
	s_waitcnt lgkmcnt(8)
	v_add_f32_e32 v66, v65, v47
	s_waitcnt lgkmcnt(5)
	v_add_f32_e32 v67, v66, v53
	s_waitcnt lgkmcnt(2)
	v_add_f32_e32 v68, v67, v59
	v_mul_f32_e32 v79, 0xbfb8aa3b, v69
	v_exp_f32_e32 v70, v79
	v_mul_f32_e32 v80, 0xbfb8aa3b, v65
	v_exp_f32_e32 v71, v80
	v_mul_f32_e32 v79, 0x3fb8aa3b, v65
	v_exp_f32_e32 v75, v79
	v_mul_f32_e32 v80, 0xbfb8aa3b, v66
	v_exp_f32_e32 v72, v80
	v_mul_f32_e32 v79, 0x3fb8aa3b, v66
	v_exp_f32_e32 v76, v79
	v_mul_f32_e32 v80, 0xbfb8aa3b, v67
	v_exp_f32_e32 v73, v80
	v_mul_f32_e32 v79, 0x3fb8aa3b, v67
	v_exp_f32_e32 v77, v79
	v_mul_f32_e32 v80, 0xbfb8aa3b, v68
	v_exp_f32_e32 v74, v80
	v_mul_f32_e32 v79, 0x3fb8aa3b, v68
	v_exp_f32_e32 v78, v79
	s_nop 0
	v_mul_f32_e32 v81, v70, v40
	v_mul_f32_e32 v85, v75, v43
	v_mul_f32_e32 v89, v75, v42
	v_mul_f32_e32 v93, v71, v44
	v_mul_f32_e32 v82, v71, v46
	v_mul_f32_e32 v86, v76, v49
	v_mul_f32_e32 v90, v76, v48
	v_mul_f32_e32 v94, v72, v50
	v_mul_f32_e32 v83, v72, v52
	v_mul_f32_e32 v87, v77, v55
	v_mul_f32_e32 v91, v77, v54
	v_mul_f32_e32 v95, v73, v56
	v_mul_f32_e32 v84, v73, v58
	s_waitcnt lgkmcnt(1)
	v_mul_f32_e32 v88, v78, v61
	v_mul_f32_e32 v92, v78, v60
	s_waitcnt lgkmcnt(0)
	v_mul_f32_e32 v96, v74, v62
	v_cvt_pk_bf16_f32 v112, v81, v82
	v_cvt_pk_bf16_f32 v113, v83, v84
	v_cvt_pk_bf16_f32 v114, v85, v86
	v_cvt_pk_bf16_f32 v115, v87, v88
	v_cvt_pk_bf16_f32 v116, v89, v90
	v_cvt_pk_bf16_f32 v117, v91, v92
	v_cvt_pk_bf16_f32 v118, v93, v94
	v_cvt_pk_bf16_f32 v119, v95, v96
	v_cvt_pk_bf16_f32 v120, v45, v51
	v_cvt_pk_bf16_f32 v121, v57, v63
	ds_write_b16 v122, v112 offset:51456
	ds_write_b16_d16_hi v122, v112 offset:51600
	ds_write_b16 v122, v113 offset:51744
	ds_write_b16_d16_hi v122, v113 offset:51888
	ds_write_b16 v122, v114 offset:53760
	ds_write_b16_d16_hi v122, v114 offset:53904
	ds_write_b16 v122, v115 offset:54048
	ds_write_b16_d16_hi v122, v115 offset:54192
	ds_write_b16 v122, v116 offset:56064
	ds_write_b16_d16_hi v122, v116 offset:56208
	ds_write_b16 v122, v117 offset:56352
	ds_write_b16_d16_hi v122, v117 offset:56496
	ds_write_b16 v122, v118 offset:60672
	ds_write_b16_d16_hi v122, v118 offset:60816
	ds_write_b16 v122, v119 offset:60960
	ds_write_b16_d16_hi v122, v119 offset:61104
	ds_write_b64 v139, v[114:115] offset:5120
	ds_write_b64 v139, v[116:117] offset:5152
	ds_write_b64 v140, v[120:121] offset:5152
	s_setprio 0
	s_branch .Lpq0_end
.Lpq0_q1:
	s_setprio 2
	ds_read2st64_b32 v[26:27], v143 offset0:97 offset1:103
	ds_read2st64_b32 v[28:29], v143 offset0:109 offset1:115
	ds_read2st64_b32 v[40:41], v143 offset0:120 offset1:121
	ds_read2st64_b32 v[42:43], v143 offset0:122 offset1:123
	ds_read2st64_b32 v[44:45], v143 offset0:124 offset1:125
	ds_read2st64_b32 v[46:47], v143 offset0:126 offset1:127
	ds_read2st64_b32 v[48:49], v143 offset0:128 offset1:129
	ds_read2st64_b32 v[50:51], v143 offset0:130 offset1:131
	ds_read2st64_b32 v[52:53], v143 offset0:132 offset1:133
	ds_read2st64_b32 v[54:55], v143 offset0:134 offset1:135
	ds_read2st64_b32 v[56:57], v143 offset0:136 offset1:137
	ds_read2st64_b32 v[58:59], v143 offset0:138 offset1:139
	ds_read2st64_b32 v[60:61], v143 offset0:140 offset1:141
	ds_read2st64_b32 v[62:63], v143 offset0:142 offset1:143
	v_lshrrev_b32_e32 v122, 1, v143
	s_waitcnt lgkmcnt(13)
	v_add_f32_e32 v69, v26, v27
	s_waitcnt lgkmcnt(12)
	v_add_f32_e32 v69, v69, v28
	v_add_f32_e32 v69, v69, v29
	s_waitcnt lgkmcnt(11)
	v_add_f32_e32 v65, v69, v41
	s_waitcnt lgkmcnt(8)
	v_add_f32_e32 v66, v65, v47
	s_waitcnt lgkmcnt(5)
	v_add_f32_e32 v67, v66, v53
	s_waitcnt lgkmcnt(2)
	v_add_f32_e32 v68, v67, v59
	v_mul_f32_e32 v79, 0xbfb8aa3b, v69
	v_exp_f32_e32 v70, v79
	v_mul_f32_e32 v80, 0xbfb8aa3b, v65
	v_exp_f32_e32 v71, v80
	v_mul_f32_e32 v79, 0x3fb8aa3b, v65
	v_exp_f32_e32 v75, v79
	v_mul_f32_e32 v80, 0xbfb8aa3b, v66
	v_exp_f32_e32 v72, v80
	v_mul_f32_e32 v79, 0x3fb8aa3b, v66
	v_exp_f32_e32 v76, v79
	v_mul_f32_e32 v80, 0xbfb8aa3b, v67
	v_exp_f32_e32 v73, v80
	v_mul_f32_e32 v79, 0x3fb8aa3b, v67
	v_exp_f32_e32 v77, v79
	v_mul_f32_e32 v80, 0xbfb8aa3b, v68
	v_exp_f32_e32 v74, v80
	v_mul_f32_e32 v79, 0x3fb8aa3b, v68
	v_exp_f32_e32 v78, v79
	s_nop 0
	v_mul_f32_e32 v81, v70, v40
	v_mul_f32_e32 v85, v75, v43
	v_mul_f32_e32 v89, v75, v42
	v_mul_f32_e32 v93, v71, v44
	v_mul_f32_e32 v82, v71, v46
	v_mul_f32_e32 v86, v76, v49
	v_mul_f32_e32 v90, v76, v48
	v_mul_f32_e32 v94, v72, v50
	v_mul_f32_e32 v83, v72, v52
	v_mul_f32_e32 v87, v77, v55
	v_mul_f32_e32 v91, v77, v54
	v_mul_f32_e32 v95, v73, v56
	v_mul_f32_e32 v84, v73, v58
	s_waitcnt lgkmcnt(1)
	v_mul_f32_e32 v88, v78, v61
	v_mul_f32_e32 v92, v78, v60
	s_waitcnt lgkmcnt(0)
	v_mul_f32_e32 v96, v74, v62
	v_cvt_pk_bf16_f32 v112, v81, v82
	v_cvt_pk_bf16_f32 v113, v83, v84
	v_cvt_pk_bf16_f32 v114, v85, v86
	v_cvt_pk_bf16_f32 v115, v87, v88
	v_cvt_pk_bf16_f32 v116, v89, v90
	v_cvt_pk_bf16_f32 v117, v91, v92
	v_cvt_pk_bf16_f32 v118, v93, v94
	v_cvt_pk_bf16_f32 v119, v95, v96
	v_cvt_pk_bf16_f32 v120, v45, v51
	v_cvt_pk_bf16_f32 v121, v57, v63
	ds_write_b16 v122, v112 offset:52032
	ds_write_b16_d16_hi v122, v112 offset:52176
	ds_write_b16 v122, v113 offset:52320
	ds_write_b16_d16_hi v122, v113 offset:52464
	ds_write_b16 v122, v114 offset:54336
	ds_write_b16_d16_hi v122, v114 offset:54480
	ds_write_b16 v122, v115 offset:54624
	ds_write_b16_d16_hi v122, v115 offset:54768
	ds_write_b16 v122, v116 offset:56640
	ds_write_b16_d16_hi v122, v116 offset:56784
	ds_write_b16 v122, v117 offset:56928
	ds_write_b16_d16_hi v122, v117 offset:57072
	ds_write_b16 v122, v118 offset:61248
	ds_write_b16_d16_hi v122, v118 offset:61392
	ds_write_b16 v122, v119 offset:61536
	ds_write_b16_d16_hi v122, v119 offset:61680
	ds_write_b64 v139, v[114:115] offset:5128
	ds_write_b64 v139, v[116:117] offset:5160
	ds_write_b64 v140, v[120:121] offset:5160
	s_setprio 0
	s_branch .Lpq0_end
.Lpq0_q2:
	s_setprio 2
	ds_read2st64_b32 v[26:27], v143 offset0:97 offset1:103
	ds_read2st64_b32 v[28:29], v143 offset0:109 offset1:115
	ds_read2st64_b32 v[30:31], v143 offset0:121 offset1:127
	ds_read2st64_b32 v[32:33], v143 offset0:133 offset1:139
	ds_read2st64_b32 v[40:41], v143 offset0:144 offset1:145
	ds_read2st64_b32 v[42:43], v143 offset0:146 offset1:147
	ds_read2st64_b32 v[44:45], v143 offset0:148 offset1:149
	ds_read2st64_b32 v[46:47], v143 offset0:150 offset1:151
	ds_read2st64_b32 v[48:49], v143 offset0:152 offset1:153
	ds_read2st64_b32 v[50:51], v143 offset0:154 offset1:155
	ds_read2st64_b32 v[52:53], v143 offset0:156 offset1:157
	ds_read2st64_b32 v[54:55], v143 offset0:158 offset1:159
	ds_read2st64_b32 v[56:57], v143 offset0:160 offset1:161
	ds_read2st64_b32 v[58:59], v143 offset0:162 offset1:163
	ds_read2st64_b32 v[60:61], v143 offset0:164 offset1:165
	s_waitcnt lgkmcnt(14)
	ds_read2st64_b32 v[62:63], v143 offset0:166 offset1:167
	v_lshrrev_b32_e32 v122, 1, v143
	v_add_f32_e32 v69, v26, v27
	s_waitcnt lgkmcnt(14)
	v_add_f32_e32 v69, v69, v28
	v_add_f32_e32 v69, v69, v29
	s_waitcnt lgkmcnt(13)
	v_add_f32_e32 v69, v69, v30
	v_add_f32_e32 v69, v69, v31
	s_waitcnt lgkmcnt(12)
	v_add_f32_e32 v69, v69, v32
	v_add_f32_e32 v69, v69, v33
	s_waitcnt lgkmcnt(11)
	v_add_f32_e32 v65, v69, v41
	s_waitcnt lgkmcnt(8)
	v_add_f32_e32 v66, v65, v47
	s_waitcnt lgkmcnt(5)
	v_add_f32_e32 v67, v66, v53
	s_waitcnt lgkmcnt(2)
	v_add_f32_e32 v68, v67, v59
	v_mul_f32_e32 v79, 0xbfb8aa3b, v69
	v_exp_f32_e32 v70, v79
	v_mul_f32_e32 v80, 0xbfb8aa3b, v65
	v_exp_f32_e32 v71, v80
	v_mul_f32_e32 v79, 0x3fb8aa3b, v65
	v_exp_f32_e32 v75, v79
	v_mul_f32_e32 v80, 0xbfb8aa3b, v66
	v_exp_f32_e32 v72, v80
	v_mul_f32_e32 v79, 0x3fb8aa3b, v66
	v_exp_f32_e32 v76, v79
	v_mul_f32_e32 v80, 0xbfb8aa3b, v67
	v_exp_f32_e32 v73, v80
	v_mul_f32_e32 v79, 0x3fb8aa3b, v67
	v_exp_f32_e32 v77, v79
	v_mul_f32_e32 v80, 0xbfb8aa3b, v68
	v_exp_f32_e32 v74, v80
	v_mul_f32_e32 v79, 0x3fb8aa3b, v68
	v_exp_f32_e32 v78, v79
	s_nop 0
	v_mul_f32_e32 v81, v70, v40
	v_mul_f32_e32 v85, v75, v43
	v_mul_f32_e32 v89, v75, v42
	v_mul_f32_e32 v93, v71, v44
	v_mul_f32_e32 v82, v71, v46
	v_mul_f32_e32 v86, v76, v49
	v_mul_f32_e32 v90, v76, v48
	v_mul_f32_e32 v94, v72, v50
	v_mul_f32_e32 v83, v72, v52
	v_mul_f32_e32 v87, v77, v55
	v_mul_f32_e32 v91, v77, v54
	v_mul_f32_e32 v95, v73, v56
	v_mul_f32_e32 v84, v73, v58
	s_waitcnt lgkmcnt(1)
	v_mul_f32_e32 v88, v78, v61
	v_mul_f32_e32 v92, v78, v60
	s_waitcnt lgkmcnt(0)
	v_mul_f32_e32 v96, v74, v62
	v_cvt_pk_bf16_f32 v112, v81, v82
	v_cvt_pk_bf16_f32 v113, v83, v84
	v_cvt_pk_bf16_f32 v114, v85, v86
	v_cvt_pk_bf16_f32 v115, v87, v88
	v_cvt_pk_bf16_f32 v116, v89, v90
	v_cvt_pk_bf16_f32 v117, v91, v92
	v_cvt_pk_bf16_f32 v118, v93, v94
	v_cvt_pk_bf16_f32 v119, v95, v96
	v_cvt_pk_bf16_f32 v120, v45, v51
	v_cvt_pk_bf16_f32 v121, v57, v63
	ds_write_b16 v122, v112 offset:52608
	ds_write_b16_d16_hi v122, v112 offset:52752
	ds_write_b16 v122, v113 offset:52896
	ds_write_b16_d16_hi v122, v113 offset:53040
	ds_write_b16 v122, v114 offset:54912
	ds_write_b16_d16_hi v122, v114 offset:55056
	ds_write_b16 v122, v115 offset:55200
	ds_write_b16_d16_hi v122, v115 offset:55344
	ds_write_b16 v122, v116 offset:57216
	ds_write_b16_d16_hi v122, v116 offset:57360
	ds_write_b16 v122, v117 offset:57504
	ds_write_b16_d16_hi v122, v117 offset:57648
	ds_write_b16 v122, v118 offset:61824
	ds_write_b16_d16_hi v122, v118 offset:61968
	ds_write_b16 v122, v119 offset:62112
	ds_write_b16_d16_hi v122, v119 offset:62256
	ds_write_b64 v139, v[114:115] offset:5136
	ds_write_b64 v139, v[116:117] offset:5168
	ds_write_b64 v140, v[120:121] offset:5168
	s_setprio 0
	s_branch .Lpq0_end
.Lpq0_q3:
	s_setprio 2
	ds_read2st64_b32 v[26:27], v143 offset0:97 offset1:103
	ds_read2st64_b32 v[28:29], v143 offset0:109 offset1:115
	ds_read2st64_b32 v[30:31], v143 offset0:121 offset1:127
	ds_read2st64_b32 v[32:33], v143 offset0:133 offset1:139
	ds_read2st64_b32 v[34:35], v143 offset0:145 offset1:151
	ds_read2st64_b32 v[36:37], v143 offset0:157 offset1:163
	ds_read2st64_b32 v[40:41], v143 offset0:168 offset1:169
	ds_read2st64_b32 v[42:43], v143 offset0:170 offset1:171
	ds_read2st64_b32 v[44:45], v143 offset0:172 offset1:173
	ds_read2st64_b32 v[46:47], v143 offset0:174 offset1:175
	ds_read2st64_b32 v[48:49], v143 offset0:176 offset1:177
	ds_read2st64_b32 v[50:51], v143 offset0:178 offset1:179
	ds_read2st64_b32 v[52:53], v143 offset0:180 offset1:181
	ds_read2st64_b32 v[54:55], v143 offset0:182 offset1:183
	ds_read2st64_b32 v[56:57], v143 offset0:184 offset1:185
	s_waitcnt lgkmcnt(14)
	ds_read2st64_b32 v[58:59], v143 offset0:186 offset1:187
	s_waitcnt lgkmcnt(14)
	ds_read2st64_b32 v[60:61], v143 offset0:188 offset1:189
	s_waitcnt lgkmcnt(14)
	ds_read2st64_b32 v[62:63], v143 offset0:190 offset1:191
	v_lshrrev_b32_e32 v122, 1, v143
	v_add_f32_e32 v69, v26, v27
	v_add_f32_e32 v69, v69, v28
	v_add_f32_e32 v69, v69, v29
	v_add_f32_e32 v69, v69, v30
	v_add_f32_e32 v69, v69, v31
	s_waitcnt lgkmcnt(14)
	v_add_f32_e32 v69, v69, v32
	v_add_f32_e32 v69, v69, v33
	s_waitcnt lgkmcnt(13)
	v_add_f32_e32 v69, v69, v34
	v_add_f32_e32 v69, v69, v35
	s_waitcnt lgkmcnt(12)
	v_add_f32_e32 v69, v69, v36
	v_add_f32_e32 v69, v69, v37
	s_waitcnt lgkmcnt(11)
	v_add_f32_e32 v65, v69, v41
	s_waitcnt lgkmcnt(8)
	v_add_f32_e32 v66, v65, v47
	s_waitcnt lgkmcnt(5)
	v_add_f32_e32 v67, v66, v53
	s_waitcnt lgkmcnt(2)
	v_add_f32_e32 v68, v67, v59
	v_mul_f32_e32 v79, 0xbfb8aa3b, v69
	v_exp_f32_e32 v70, v79
	v_mul_f32_e32 v80, 0xbfb8aa3b, v65
	v_exp_f32_e32 v71, v80
	v_mul_f32_e32 v79, 0x3fb8aa3b, v65
	v_exp_f32_e32 v75, v79
	v_mul_f32_e32 v80, 0xbfb8aa3b, v66
	v_exp_f32_e32 v72, v80
	v_mul_f32_e32 v79, 0x3fb8aa3b, v66
	v_exp_f32_e32 v76, v79
	v_mul_f32_e32 v80, 0xbfb8aa3b, v67
	v_exp_f32_e32 v73, v80
	v_mul_f32_e32 v79, 0x3fb8aa3b, v67
	v_exp_f32_e32 v77, v79
	v_mul_f32_e32 v80, 0xbfb8aa3b, v68
	v_exp_f32_e32 v74, v80
	v_mul_f32_e32 v79, 0x3fb8aa3b, v68
	v_exp_f32_e32 v78, v79
	s_nop 0
	v_mul_f32_e32 v81, v70, v40
	v_mul_f32_e32 v85, v75, v43
	v_mul_f32_e32 v89, v75, v42
	v_mul_f32_e32 v93, v71, v44
	v_mul_f32_e32 v82, v71, v46
	v_mul_f32_e32 v86, v76, v49
	v_mul_f32_e32 v90, v76, v48
	v_mul_f32_e32 v94, v72, v50
	v_mul_f32_e32 v83, v72, v52
	v_mul_f32_e32 v87, v77, v55
	v_mul_f32_e32 v91, v77, v54
	v_mul_f32_e32 v95, v73, v56
	v_mul_f32_e32 v84, v73, v58
	s_waitcnt lgkmcnt(1)
	v_mul_f32_e32 v88, v78, v61
	v_mul_f32_e32 v92, v78, v60
	s_waitcnt lgkmcnt(0)
	v_mul_f32_e32 v96, v74, v62
	v_cvt_pk_bf16_f32 v112, v81, v82
	v_cvt_pk_bf16_f32 v113, v83, v84
	v_cvt_pk_bf16_f32 v114, v85, v86
	v_cvt_pk_bf16_f32 v115, v87, v88
	v_cvt_pk_bf16_f32 v116, v89, v90
	v_cvt_pk_bf16_f32 v117, v91, v92
	v_cvt_pk_bf16_f32 v118, v93, v94
	v_cvt_pk_bf16_f32 v119, v95, v96
	v_cvt_pk_bf16_f32 v120, v45, v51
	v_cvt_pk_bf16_f32 v121, v57, v63
	ds_write_b16 v122, v112 offset:53184
	ds_write_b16_d16_hi v122, v112 offset:53328
	ds_write_b16 v122, v113 offset:53472
	ds_write_b16_d16_hi v122, v113 offset:53616
	ds_write_b16 v122, v114 offset:55488
	ds_write_b16_d16_hi v122, v114 offset:55632
	ds_write_b16 v122, v115 offset:55776
	ds_write_b16_d16_hi v122, v115 offset:55920
	ds_write_b16 v122, v116 offset:57792
	ds_write_b16_d16_hi v122, v116 offset:57936
	ds_write_b16 v122, v117 offset:58080
	ds_write_b16_d16_hi v122, v117 offset:58224
	ds_write_b16 v122, v118 offset:62400
	ds_write_b16_d16_hi v122, v118 offset:62544
	ds_write_b16 v122, v119 offset:62688
	ds_write_b16_d16_hi v122, v119 offset:62832
	ds_write_b64 v139, v[114:115] offset:5144
	ds_write_b64 v139, v[116:117] offset:5176
	ds_write_b64 v140, v[120:121] offset:5176
	v_add_u32_e32 v123, 0x18e00, v143
	ds_write_b32 v123, v74
	s_setprio 0
	s_branch .Lpq0_end

.Lsx1_c:
	s_or_b64 exec, exec, s[74:75]
	v_mov_b32_e32 v22, 0
	v_mov_b32_e32 v23, 0
	v_mov_b32_e32 v24, 0
	v_mov_b32_e32 v25, 0
	s_and_saveexec_b64 s[74:75], s[56:57]
	s_cbranch_execz .LBB0_432
	ds_read_b128 v[48:51], v174
	ds_read_b128 v[60:63], v192 offset:51456
	ds_read_b128 v[52:55], v174 offset:64
	ds_read_b128 v[64:67], v192 offset:51520
	ds_read_b128 v[56:59], v175 offset:5120
	ds_read_b128 v[68:71], v199
	ds_read_b128 v[72:75], v192 offset:60672
	ds_read_b128 v[76:79], v192 offset:60736
	ds_read_b128 v[80:83], v151
	ds_read_b128 v[84:87], v151 offset:16
	ds_read_b128 v[88:91], v151 offset:32
	ds_read_b128 v[92:95], v151 offset:48
	s_cmp_gt_u32 s36, 62
	s_cbranch_scc1 .Lcp1
	s_waitcnt vmcnt(4)
	v_lshlrev_b32_e32 v136, 16, v6
	v_and_b32_e32 v137, 0xffff0000, v6
	v_pk_mul_f32 v[124:125], v[102:103], v[136:137]
	s_waitcnt vmcnt(2)
	v_lshlrev_b32_e32 v126, 16, v8
	s_waitcnt vmcnt(0)
	v_pk_mul_f32 v[124:125], v[110:111], v[124:125] op_sel_hi:[0,1]
	v_and_b32_e32 v127, 0xffff0000, v8
	v_lshlrev_b32_e32 v130, 16, v9
	v_and_b32_e32 v131, 0xffff0000, v9
	v_pk_add_f32 v[128:129], v[130:131], -1.0 op_sel_hi:[1,0]
	v_pk_mul_f32 v[130:131], v[130:131], v[124:125] neg_lo:[0,1] neg_hi:[0,1]
	v_pk_fma_f32 v[128:129], v[104:105], v[128:129], 1.0 op_sel_hi:[1,1,0]
	s_nop 0
	v_pk_mul_f32 v[128:129], v[128:129], v[136:137]
	v_lshlrev_b32_e32 v132, 16, v5
	v_and_b32_e32 v133, 0xffff0000, v5
	v_lshlrev_b32_e32 v134, 16, v7
	v_and_b32_e32 v135, 0xffff0000, v7
.Lcp1:
	s_waitcnt lgkmcnt(10)
	v_mfma_f32_16x16x32_bf16 v[30:33], v[48:51], v[60:63], 0
	s_waitcnt lgkmcnt(8)
	v_mfma_f32_16x16x32_bf16 v[30:33], v[52:55], v[64:67], v[30:33]
	s_waitcnt lgkmcnt(6)
	v_mfma_f32_16x16x32_bf16 v[30:33], v[56:59], v[68:71], v[30:33]
	s_waitcnt lgkmcnt(5)
	v_mfma_f32_16x16x32_bf16 v[22:25], v[48:51], v[72:75], 0
	s_waitcnt lgkmcnt(4)
	v_mfma_f32_16x16x32_bf16 v[22:25], v[52:55], v[76:79], v[22:25]
	s_cmp_gt_u32 s36, 61
	s_cbranch_scc1 .Lis1bw
	s_add_i32 s24, s19, 0xffffffb0
	s_add_i32 s25, s21, 64
	s_and_b64 s[98:99], s[12:13], exec
	s_cselect_b32 s24, s25, s24
	v_lshl_add_u32 v194, s24, 6, v183
	v_lshlrev_b32_e32 v112, 1, v194
	global_load_dword v0, v112, s[44:45]
	global_load_dword v1, v112, s[42:43]
	global_load_dword v2, v112, s[0:1]
	global_load_dword v4, v112, s[76:77]
	global_load_dword v3, v112, s[34:35]
	v_add_u32_e32 v194, s24, v184
	v_lshlrev_b32_e32 v114, 2, v194
	global_load_dword v108, v114, s[40:41]
	s_branch .Lis1b

.Lis1b:
	v_cvt_pk_bf16_f32 v240, v236, v237
	global_store_dword v[238:239], v240, off
	s_setprio 3
	s_waitcnt lgkmcnt(0)
	s_nop 6
	v_fmac_f32_dpp v30, v30, v80 row_newbcast:0 row_mask:0xf bank_mask:0xf
	v_fmac_f32_dpp v31, v31, v80 row_newbcast:0 row_mask:0xf bank_mask:0xf
	v_fmac_f32_dpp v32, v32, v80 row_newbcast:0 row_mask:0xf bank_mask:0xf
	v_fmac_f32_dpp v33, v33, v80 row_newbcast:0 row_mask:0xf bank_mask:0xf
	v_fmac_f32_dpp v30, v30, v81 row_newbcast:1 row_mask:0xf bank_mask:0xf
	v_fmac_f32_dpp v31, v31, v81 row_newbcast:1 row_mask:0xf bank_mask:0xf
	v_fmac_f32_dpp v32, v32, v81 row_newbcast:1 row_mask:0xf bank_mask:0xf
	v_fmac_f32_dpp v33, v33, v81 row_newbcast:1 row_mask:0xf bank_mask:0xf
	v_fmac_f32_dpp v30, v30, v82 row_newbcast:2 row_mask:0xf bank_mask:0xf
	v_fmac_f32_dpp v31, v31, v82 row_newbcast:2 row_mask:0xf bank_mask:0xf
	v_fmac_f32_dpp v32, v32, v82 row_newbcast:2 row_mask:0xf bank_mask:0xf
	v_fmac_f32_dpp v33, v33, v82 row_newbcast:2 row_mask:0xf bank_mask:0xf
	v_fmac_f32_dpp v30, v30, v83 row_newbcast:3 row_mask:0xf bank_mask:0xf
	v_fmac_f32_dpp v31, v31, v83 row_newbcast:3 row_mask:0xf bank_mask:0xf
	v_fmac_f32_dpp v32, v32, v83 row_newbcast:3 row_mask:0xf bank_mask:0xf
	v_fmac_f32_dpp v33, v33, v83 row_newbcast:3 row_mask:0xf bank_mask:0xf
	v_fmac_f32_dpp v30, v30, v84 row_newbcast:4 row_mask:0xf bank_mask:0xf
	v_fmac_f32_dpp v31, v31, v84 row_newbcast:4 row_mask:0xf bank_mask:0xf
	v_fmac_f32_dpp v32, v32, v84 row_newbcast:4 row_mask:0xf bank_mask:0xf
	v_fmac_f32_dpp v33, v33, v84 row_newbcast:4 row_mask:0xf bank_mask:0xf
	v_fmac_f32_dpp v30, v30, v85 row_newbcast:5 row_mask:0xf bank_mask:0xf
	v_fmac_f32_dpp v31, v31, v85 row_newbcast:5 row_mask:0xf bank_mask:0xf
	v_fmac_f32_dpp v32, v32, v85 row_newbcast:5 row_mask:0xf bank_mask:0xf
	v_fmac_f32_dpp v33, v33, v85 row_newbcast:5 row_mask:0xf bank_mask:0xf
	v_fmac_f32_dpp v30, v30, v86 row_newbcast:6 row_mask:0xf bank_mask:0xf
	v_fmac_f32_dpp v31, v31, v86 row_newbcast:6 row_mask:0xf bank_mask:0xf
	v_fmac_f32_dpp v32, v32, v86 row_newbcast:6 row_mask:0xf bank_mask:0xf
	v_fmac_f32_dpp v33, v33, v86 row_newbcast:6 row_mask:0xf bank_mask:0xf
	v_fmac_f32_dpp v30, v30, v87 row_newbcast:7 row_mask:0xf bank_mask:0xf
	v_fmac_f32_dpp v31, v31, v87 row_newbcast:7 row_mask:0xf bank_mask:0xf
	v_fmac_f32_dpp v32, v32, v87 row_newbcast:7 row_mask:0xf bank_mask:0xf
	v_fmac_f32_dpp v33, v33, v87 row_newbcast:7 row_mask:0xf bank_mask:0xf
	v_fmac_f32_dpp v30, v30, v88 row_newbcast:8 row_mask:0xf bank_mask:0xf
	v_fmac_f32_dpp v31, v31, v88 row_newbcast:8 row_mask:0xf bank_mask:0xf
	v_fmac_f32_dpp v32, v32, v88 row_newbcast:8 row_mask:0xf bank_mask:0xf
	v_fmac_f32_dpp v33, v33, v88 row_newbcast:8 row_mask:0xf bank_mask:0xf
	v_fmac_f32_dpp v30, v30, v89 row_newbcast:9 row_mask:0xf bank_mask:0xf
	v_fmac_f32_dpp v31, v31, v89 row_newbcast:9 row_mask:0xf bank_mask:0xf
	v_fmac_f32_dpp v32, v32, v89 row_newbcast:9 row_mask:0xf bank_mask:0xf
	v_fmac_f32_dpp v33, v33, v89 row_newbcast:9 row_mask:0xf bank_mask:0xf
	v_fmac_f32_dpp v30, v30, v90 row_newbcast:10 row_mask:0xf bank_mask:0xf
	v_fmac_f32_dpp v31, v31, v90 row_newbcast:10 row_mask:0xf bank_mask:0xf
	v_fmac_f32_dpp v32, v32, v90 row_newbcast:10 row_mask:0xf bank_mask:0xf
	v_fmac_f32_dpp v33, v33, v90 row_newbcast:10 row_mask:0xf bank_mask:0xf
	v_fmac_f32_dpp v30, v30, v91 row_newbcast:11 row_mask:0xf bank_mask:0xf
	v_fmac_f32_dpp v31, v31, v91 row_newbcast:11 row_mask:0xf bank_mask:0xf
	v_fmac_f32_dpp v32, v32, v91 row_newbcast:11 row_mask:0xf bank_mask:0xf
	v_fmac_f32_dpp v33, v33, v91 row_newbcast:11 row_mask:0xf bank_mask:0xf
	v_fmac_f32_dpp v30, v30, v92 row_newbcast:12 row_mask:0xf bank_mask:0xf
	v_fmac_f32_dpp v31, v31, v92 row_newbcast:12 row_mask:0xf bank_mask:0xf
	v_fmac_f32_dpp v32, v32, v92 row_newbcast:12 row_mask:0xf bank_mask:0xf
	v_fmac_f32_dpp v33, v33, v92 row_newbcast:12 row_mask:0xf bank_mask:0xf
	v_fmac_f32_dpp v30, v30, v93 row_newbcast:13 row_mask:0xf bank_mask:0xf
	v_fmac_f32_dpp v31, v31, v93 row_newbcast:13 row_mask:0xf bank_mask:0xf
	v_fmac_f32_dpp v32, v32, v93 row_newbcast:13 row_mask:0xf bank_mask:0xf
	v_fmac_f32_dpp v33, v33, v93 row_newbcast:13 row_mask:0xf bank_mask:0xf
	v_fmac_f32_dpp v30, v30, v94 row_newbcast:14 row_mask:0xf bank_mask:0xf
	v_fmac_f32_dpp v31, v31, v94 row_newbcast:14 row_mask:0xf bank_mask:0xf
	v_fmac_f32_dpp v32, v32, v94 row_newbcast:14 row_mask:0xf bank_mask:0xf
	v_fmac_f32_dpp v33, v33, v94 row_newbcast:14 row_mask:0xf bank_mask:0xf
	v_lshrrev_b32_e32 v82, 6, v198
	v_mul_u32_u24_e32 v82, 0x500, v82
	v_mad_u32_u24 v82, v145, 20, v82
	v_and_b32_e32 v83, 15, v198
	v_lshl_add_u32 v82, v83, 1, v82
	v_add_u32_e32 v82, 0x10a00, v82
	v_cvt_pk_bf16_f32 v80, v30, v31
	v_cvt_pk_bf16_f32 v81, v32, v33
	ds_write_b16 v82, v80 offset:5120
	ds_write_b16_d16_hi v82, v80 offset:5200
	ds_write_b16 v82, v81 offset:5280
	ds_write_b16_d16_hi v82, v81 offset:5360
	s_setprio 1
.LBB0_432:
	s_or_b64 exec, exec, s[74:75]
	s_waitcnt lgkmcnt(0)
.LBB0_434:
	v_lshrrev_b32_e32 v122, 6, v198
	s_nop 0
	v_readfirstlane_b32 s98, v122
	s_nop 3
	s_cmpk_lt_u32 s20, 0x7f
	s_cbranch_scc0 .Lpq1_end
	s_cmp_eq_u32 s98, 0
	s_cbranch_scc1 .Lpq1_q0
	s_cmp_eq_u32 s98, 1
	s_cbranch_scc1 .Lpq1_q1
	s_cmp_eq_u32 s98, 2
	s_cbranch_scc1 .Lpq1_q2
	s_cmp_eq_u32 s98, 3
	s_cbranch_scc1 .Lpq1_q3
	s_branch .Lpq1_end
.Lpq1_q0:
	s_setprio 2
	ds_read2st64_b32 v[40:41], v143 offset0:0 offset1:1
	ds_read2st64_b32 v[42:43], v143 offset0:2 offset1:3
	ds_read2st64_b32 v[44:45], v143 offset0:4 offset1:5
	ds_read2st64_b32 v[46:47], v143 offset0:6 offset1:7
	ds_read2st64_b32 v[48:49], v143 offset0:8 offset1:9
	ds_read2st64_b32 v[50:51], v143 offset0:10 offset1:11
	ds_read2st64_b32 v[52:53], v143 offset0:12 offset1:13
	ds_read2st64_b32 v[54:55], v143 offset0:14 offset1:15
	ds_read2st64_b32 v[56:57], v143 offset0:16 offset1:17
	ds_read2st64_b32 v[58:59], v143 offset0:18 offset1:19
	ds_read2st64_b32 v[60:61], v143 offset0:20 offset1:21
	ds_read2st64_b32 v[62:63], v143 offset0:22 offset1:23
	v_lshrrev_b32_e32 v122, 1, v143
	v_mov_b32_e32 v69, 0
	s_waitcnt lgkmcnt(11)
	v_add_f32_e32 v65, v69, v41
	s_waitcnt lgkmcnt(8)
	v_add_f32_e32 v66, v65, v47
	s_waitcnt lgkmcnt(5)
	v_add_f32_e32 v67, v66, v53
	s_waitcnt lgkmcnt(2)
	v_add_f32_e32 v68, v67, v59
	v_mul_f32_e32 v79, 0xbfb8aa3b, v69
	v_exp_f32_e32 v70, v79
	v_mul_f32_e32 v80, 0xbfb8aa3b, v65
	v_exp_f32_e32 v71, v80
	v_mul_f32_e32 v79, 0x3fb8aa3b, v65
	v_exp_f32_e32 v75, v79
	v_mul_f32_e32 v80, 0xbfb8aa3b, v66
	v_exp_f32_e32 v72, v80
	v_mul_f32_e32 v79, 0x3fb8aa3b, v66
	v_exp_f32_e32 v76, v79
	v_mul_f32_e32 v80, 0xbfb8aa3b, v67
	v_exp_f32_e32 v73, v80
	v_mul_f32_e32 v79, 0x3fb8aa3b, v67
	v_exp_f32_e32 v77, v79
	v_mul_f32_e32 v80, 0xbfb8aa3b, v68
	v_exp_f32_e32 v74, v80
	v_mul_f32_e32 v79, 0x3fb8aa3b, v68
	v_exp_f32_e32 v78, v79
	s_nop 0
	v_mul_f32_e32 v81, v70, v40
	v_mul_f32_e32 v85, v75, v43
	v_mul_f32_e32 v89, v75, v42
	v_mul_f32_e32 v93, v71, v44
	v_mul_f32_e32 v82, v71, v46
	v_mul_f32_e32 v86, v76, v49
	v_mul_f32_e32 v90, v76, v48
	v_mul_f32_e32 v94, v72, v50
	v_mul_f32_e32 v83, v72, v52
	v_mul_f32_e32 v87, v77, v55
	v_mul_f32_e32 v91, v77, v54
	v_mul_f32_e32 v95, v73, v56
	v_mul_f32_e32 v84, v73, v58
	s_waitcnt lgkmcnt(1)
	v_mul_f32_e32 v88, v78, v61
	v_mul_f32_e32 v92, v78, v60
	s_waitcnt lgkmcnt(0)
	v_mul_f32_e32 v96, v74, v62
	v_cvt_pk_bf16_f32 v112, v81, v82
	v_cvt_pk_bf16_f32 v113, v83, v84
	v_cvt_pk_bf16_f32 v114, v85, v86
	v_cvt_pk_bf16_f32 v115, v87, v88
	v_cvt_pk_bf16_f32 v116, v89, v90
	v_cvt_pk_bf16_f32 v117, v91, v92
	v_cvt_pk_bf16_f32 v118, v93, v94
	v_cvt_pk_bf16_f32 v119, v95, v96
	v_cvt_pk_bf16_f32 v120, v45, v51
	v_cvt_pk_bf16_f32 v121, v57, v63
	ds_write_b16 v122, v112 offset:49152
	ds_write_b16_d16_hi v122, v112 offset:49296
	ds_write_b16 v122, v113 offset:49440
	ds_write_b16_d16_hi v122, v113 offset:49584
	ds_write_b16 v122, v114 offset:53760
	ds_write_b16_d16_hi v122, v114 offset:53904
	ds_write_b16 v122, v115 offset:54048
	ds_write_b16_d16_hi v122, v115 offset:54192
	ds_write_b16 v122, v116 offset:56064
	ds_write_b16_d16_hi v122, v116 offset:56208
	ds_write_b16 v122, v117 offset:56352
	ds_write_b16_d16_hi v122, v117 offset:56496
	ds_write_b16 v122, v118 offset:58368
	ds_write_b16_d16_hi v122, v118 offset:58512
	ds_write_b16 v122, v119 offset:58656
	ds_write_b16_d16_hi v122, v119 offset:58800
	ds_write_b64 v139, v[114:115] offset:0
	ds_write_b64 v139, v[116:117] offset:32
	ds_write_b64 v140, v[120:121] offset:32
	s_setprio 0
	s_branch .Lpq1_end
.Lpq1_q1:
	s_setprio 2
	ds_read2st64_b32 v[26:27], v143 offset0:1 offset1:7
	ds_read2st64_b32 v[28:29], v143 offset0:13 offset1:19
	ds_read2st64_b32 v[40:41], v143 offset0:24 offset1:25
	ds_read2st64_b32 v[42:43], v143 offset0:26 offset1:27
	ds_read2st64_b32 v[44:45], v143 offset0:28 offset1:29
	ds_read2st64_b32 v[46:47], v143 offset0:30 offset1:31
	ds_read2st64_b32 v[48:49], v143 offset0:32 offset1:33
	ds_read2st64_b32 v[50:51], v143 offset0:34 offset1:35
	ds_read2st64_b32 v[52:53], v143 offset0:36 offset1:37
	ds_read2st64_b32 v[54:55], v143 offset0:38 offset1:39
	ds_read2st64_b32 v[56:57], v143 offset0:40 offset1:41
	ds_read2st64_b32 v[58:59], v143 offset0:42 offset1:43
	ds_read2st64_b32 v[60:61], v143 offset0:44 offset1:45
	ds_read2st64_b32 v[62:63], v143 offset0:46 offset1:47
	v_lshrrev_b32_e32 v122, 1, v143
	s_waitcnt lgkmcnt(13)
	v_add_f32_e32 v69, v26, v27
	s_waitcnt lgkmcnt(12)
	v_add_f32_e32 v69, v69, v28
	v_add_f32_e32 v69, v69, v29
	s_waitcnt lgkmcnt(11)
	v_add_f32_e32 v65, v69, v41
	s_waitcnt lgkmcnt(8)
	v_add_f32_e32 v66, v65, v47
	s_waitcnt lgkmcnt(5)
	v_add_f32_e32 v67, v66, v53
	s_waitcnt lgkmcnt(2)
	v_add_f32_e32 v68, v67, v59
	v_mul_f32_e32 v79, 0xbfb8aa3b, v69
	v_exp_f32_e32 v70, v79
	v_mul_f32_e32 v80, 0xbfb8aa3b, v65
	v_exp_f32_e32 v71, v80
	v_mul_f32_e32 v79, 0x3fb8aa3b, v65
	v_exp_f32_e32 v75, v79
	v_mul_f32_e32 v80, 0xbfb8aa3b, v66
	v_exp_f32_e32 v72, v80
	v_mul_f32_e32 v79, 0x3fb8aa3b, v66
	v_exp_f32_e32 v76, v79
	v_mul_f32_e32 v80, 0xbfb8aa3b, v67
	v_exp_f32_e32 v73, v80
	v_mul_f32_e32 v79, 0x3fb8aa3b, v67
	v_exp_f32_e32 v77, v79
	v_mul_f32_e32 v80, 0xbfb8aa3b, v68
	v_exp_f32_e32 v74, v80
	v_mul_f32_e32 v79, 0x3fb8aa3b, v68
	v_exp_f32_e32 v78, v79
	s_nop 0
	v_mul_f32_e32 v81, v70, v40
	v_mul_f32_e32 v85, v75, v43
	v_mul_f32_e32 v89, v75, v42
	v_mul_f32_e32 v93, v71, v44
	v_mul_f32_e32 v82, v71, v46
	v_mul_f32_e32 v86, v76, v49
	v_mul_f32_e32 v90, v76, v48
	v_mul_f32_e32 v94, v72, v50
	v_mul_f32_e32 v83, v72, v52
	v_mul_f32_e32 v87, v77, v55
	v_mul_f32_e32 v91, v77, v54
	v_mul_f32_e32 v95, v73, v56
	v_mul_f32_e32 v84, v73, v58
	s_waitcnt lgkmcnt(1)
	v_mul_f32_e32 v88, v78, v61
	v_mul_f32_e32 v92, v78, v60
	s_waitcnt lgkmcnt(0)
	v_mul_f32_e32 v96, v74, v62
	v_cvt_pk_bf16_f32 v112, v81, v82
	v_cvt_pk_bf16_f32 v113, v83, v84
	v_cvt_pk_bf16_f32 v114, v85, v86
	v_cvt_pk_bf16_f32 v115, v87, v88
	v_cvt_pk_bf16_f32 v116, v89, v90
	v_cvt_pk_bf16_f32 v117, v91, v92
	v_cvt_pk_bf16_f32 v118, v93, v94
	v_cvt_pk_bf16_f32 v119, v95, v96
	v_cvt_pk_bf16_f32 v120, v45, v51
	v_cvt_pk_bf16_f32 v121, v57, v63
	ds_write_b16 v122, v112 offset:49728
	ds_write_b16_d16_hi v122, v112 offset:49872
	ds_write_b16 v122, v113 offset:50016
	ds_write_b16_d16_hi v122, v113 offset:50160
	ds_write_b16 v122, v114 offset:54336
	ds_write_b16_d16_hi v122, v114 offset:54480
	ds_write_b16 v122, v115 offset:54624
	ds_write_b16_d16_hi v122, v115 offset:54768
	ds_write_b16 v122, v116 offset:56640
	ds_write_b16_d16_hi v122, v116 offset:56784
	ds_write_b16 v122, v117 offset:56928
	ds_write_b16_d16_hi v122, v117 offset:57072
	ds_write_b16 v122, v118 offset:58944
	ds_write_b16_d16_hi v122, v118 offset:59088
	ds_write_b16 v122, v119 offset:59232
	ds_write_b16_d16_hi v122, v119 offset:59376
	ds_write_b64 v139, v[114:115] offset:8
	ds_write_b64 v139, v[116:117] offset:40
	ds_write_b64 v140, v[120:121] offset:40
	s_setprio 0
	s_branch .Lpq1_end
.Lpq1_q2:
	s_setprio 2
	ds_read2st64_b32 v[26:27], v143 offset0:1 offset1:7
	ds_read2st64_b32 v[28:29], v143 offset0:13 offset1:19
	ds_read2st64_b32 v[30:31], v143 offset0:25 offset1:31
	ds_read2st64_b32 v[32:33], v143 offset0:37 offset1:43
	ds_read2st64_b32 v[40:41], v143 offset0:48 offset1:49
	ds_read2st64_b32 v[42:43], v143 offset0:50 offset1:51
	ds_read2st64_b32 v[44:45], v143 offset0:52 offset1:53
	ds_read2st64_b32 v[46:47], v143 offset0:54 offset1:55
	ds_read2st64_b32 v[48:49], v143 offset0:56 offset1:57
	ds_read2st64_b32 v[50:51], v143 offset0:58 offset1:59
	ds_read2st64_b32 v[52:53], v143 offset0:60 offset1:61
	ds_read2st64_b32 v[54:55], v143 offset0:62 offset1:63
	ds_read2st64_b32 v[56:57], v143 offset0:64 offset1:65
	ds_read2st64_b32 v[58:59], v143 offset0:66 offset1:67
	ds_read2st64_b32 v[60:61], v143 offset0:68 offset1:69
	s_waitcnt lgkmcnt(14)
	ds_read2st64_b32 v[62:63], v143 offset0:70 offset1:71
	v_lshrrev_b32_e32 v122, 1, v143
	v_add_f32_e32 v69, v26, v27
	s_waitcnt lgkmcnt(14)
	v_add_f32_e32 v69, v69, v28
	v_add_f32_e32 v69, v69, v29
	s_waitcnt lgkmcnt(13)
	v_add_f32_e32 v69, v69, v30
	v_add_f32_e32 v69, v69, v31
	s_waitcnt lgkmcnt(12)
	v_add_f32_e32 v69, v69, v32
	v_add_f32_e32 v69, v69, v33
	s_waitcnt lgkmcnt(11)
	v_add_f32_e32 v65, v69, v41
	s_waitcnt lgkmcnt(8)
	v_add_f32_e32 v66, v65, v47
	s_waitcnt lgkmcnt(5)
	v_add_f32_e32 v67, v66, v53
	s_waitcnt lgkmcnt(2)
	v_add_f32_e32 v68, v67, v59
	v_mul_f32_e32 v79, 0xbfb8aa3b, v69
	v_exp_f32_e32 v70, v79
	v_mul_f32_e32 v80, 0xbfb8aa3b, v65
	v_exp_f32_e32 v71, v80
	v_mul_f32_e32 v79, 0x3fb8aa3b, v65
	v_exp_f32_e32 v75, v79
	v_mul_f32_e32 v80, 0xbfb8aa3b, v66
	v_exp_f32_e32 v72, v80
	v_mul_f32_e32 v79, 0x3fb8aa3b, v66
	v_exp_f32_e32 v76, v79
	v_mul_f32_e32 v80, 0xbfb8aa3b, v67
	v_exp_f32_e32 v73, v80
	v_mul_f32_e32 v79, 0x3fb8aa3b, v67
	v_exp_f32_e32 v77, v79
	v_mul_f32_e32 v80, 0xbfb8aa3b, v68
	v_exp_f32_e32 v74, v80
	v_mul_f32_e32 v79, 0x3fb8aa3b, v68
	v_exp_f32_e32 v78, v79
	s_nop 0
	v_mul_f32_e32 v81, v70, v40
	v_mul_f32_e32 v85, v75, v43
	v_mul_f32_e32 v89, v75, v42
	v_mul_f32_e32 v93, v71, v44
	v_mul_f32_e32 v82, v71, v46
	v_mul_f32_e32 v86, v76, v49
	v_mul_f32_e32 v90, v76, v48
	v_mul_f32_e32 v94, v72, v50
	v_mul_f32_e32 v83, v72, v52
	v_mul_f32_e32 v87, v77, v55
	v_mul_f32_e32 v91, v77, v54
	v_mul_f32_e32 v95, v73, v56
	v_mul_f32_e32 v84, v73, v58
	s_waitcnt lgkmcnt(1)
	v_mul_f32_e32 v88, v78, v61
	v_mul_f32_e32 v92, v78, v60
	s_waitcnt lgkmcnt(0)
	v_mul_f32_e32 v96, v74, v62
	v_cvt_pk_bf16_f32 v112, v81, v82
	v_cvt_pk_bf16_f32 v113, v83, v84
	v_cvt_pk_bf16_f32 v114, v85, v86
	v_cvt_pk_bf16_f32 v115, v87, v88
	v_cvt_pk_bf16_f32 v116, v89, v90
	v_cvt_pk_bf16_f32 v117, v91, v92
	v_cvt_pk_bf16_f32 v118, v93, v94
	v_cvt_pk_bf16_f32 v119, v95, v96
	v_cvt_pk_bf16_f32 v120, v45, v51
	v_cvt_pk_bf16_f32 v121, v57, v63
	ds_write_b16 v122, v112 offset:50304
	ds_write_b16_d16_hi v122, v112 offset:50448
	ds_write_b16 v122, v113 offset:50592
	ds_write_b16_d16_hi v122, v113 offset:50736
	ds_write_b16 v122, v114 offset:54912
	ds_write_b16_d16_hi v122, v114 offset:55056
	ds_write_b16 v122, v115 offset:55200
	ds_write_b16_d16_hi v122, v115 offset:55344
	ds_write_b16 v122, v116 offset:57216
	ds_write_b16_d16_hi v122, v116 offset:57360
	ds_write_b16 v122, v117 offset:57504
	ds_write_b16_d16_hi v122, v117 offset:57648
	ds_write_b16 v122, v118 offset:59520
	ds_write_b16_d16_hi v122, v118 offset:59664
	ds_write_b16 v122, v119 offset:59808
	ds_write_b16_d16_hi v122, v119 offset:59952
	ds_write_b64 v139, v[114:115] offset:16
	ds_write_b64 v139, v[116:117] offset:48
	ds_write_b64 v140, v[120:121] offset:48
	s_setprio 0
	s_branch .Lpq1_end
.Lpq1_q3:
	s_setprio 2
	ds_read2st64_b32 v[26:27], v143 offset0:1 offset1:7
	ds_read2st64_b32 v[28:29], v143 offset0:13 offset1:19
	ds_read2st64_b32 v[30:31], v143 offset0:25 offset1:31
	ds_read2st64_b32 v[32:33], v143 offset0:37 offset1:43
	ds_read2st64_b32 v[34:35], v143 offset0:49 offset1:55
	ds_read2st64_b32 v[36:37], v143 offset0:61 offset1:67
	ds_read2st64_b32 v[40:41], v143 offset0:72 offset1:73
	ds_read2st64_b32 v[42:43], v143 offset0:74 offset1:75
	ds_read2st64_b32 v[44:45], v143 offset0:76 offset1:77
	ds_read2st64_b32 v[46:47], v143 offset0:78 offset1:79
	ds_read2st64_b32 v[48:49], v143 offset0:80 offset1:81
	ds_read2st64_b32 v[50:51], v143 offset0:82 offset1:83
	ds_read2st64_b32 v[52:53], v143 offset0:84 offset1:85
	ds_read2st64_b32 v[54:55], v143 offset0:86 offset1:87
	ds_read2st64_b32 v[56:57], v143 offset0:88 offset1:89
	s_waitcnt lgkmcnt(14)
	ds_read2st64_b32 v[58:59], v143 offset0:90 offset1:91
	s_waitcnt lgkmcnt(14)
	ds_read2st64_b32 v[60:61], v143 offset0:92 offset1:93
	s_waitcnt lgkmcnt(14)
	ds_read2st64_b32 v[62:63], v143 offset0:94 offset1:95
	v_lshrrev_b32_e32 v122, 1, v143
	v_add_f32_e32 v69, v26, v27
	v_add_f32_e32 v69, v69, v28
	v_add_f32_e32 v69, v69, v29
	v_add_f32_e32 v69, v69, v30
	v_add_f32_e32 v69, v69, v31
	s_waitcnt lgkmcnt(14)
	v_add_f32_e32 v69, v69, v32
	v_add_f32_e32 v69, v69, v33
	s_waitcnt lgkmcnt(13)
	v_add_f32_e32 v69, v69, v34
	v_add_f32_e32 v69, v69, v35
	s_waitcnt lgkmcnt(12)
	v_add_f32_e32 v69, v69, v36
	v_add_f32_e32 v69, v69, v37
	s_waitcnt lgkmcnt(11)
	v_add_f32_e32 v65, v69, v41
	s_waitcnt lgkmcnt(8)
	v_add_f32_e32 v66, v65, v47
	s_waitcnt lgkmcnt(5)
	v_add_f32_e32 v67, v66, v53
	s_waitcnt lgkmcnt(2)
	v_add_f32_e32 v68, v67, v59
	v_mul_f32_e32 v79, 0xbfb8aa3b, v69
	v_exp_f32_e32 v70, v79
	v_mul_f32_e32 v80, 0xbfb8aa3b, v65
	v_exp_f32_e32 v71, v80
	v_mul_f32_e32 v79, 0x3fb8aa3b, v65
	v_exp_f32_e32 v75, v79
	v_mul_f32_e32 v80, 0xbfb8aa3b, v66
	v_exp_f32_e32 v72, v80
	v_mul_f32_e32 v79, 0x3fb8aa3b, v66
	v_exp_f32_e32 v76, v79
	v_mul_f32_e32 v80, 0xbfb8aa3b, v67
	v_exp_f32_e32 v73, v80
	v_mul_f32_e32 v79, 0x3fb8aa3b, v67
	v_exp_f32_e32 v77, v79
	v_mul_f32_e32 v80, 0xbfb8aa3b, v68
	v_exp_f32_e32 v74, v80
	v_mul_f32_e32 v79, 0x3fb8aa3b, v68
	v_exp_f32_e32 v78, v79
	s_nop 0
	v_mul_f32_e32 v81, v70, v40
	v_mul_f32_e32 v85, v75, v43
	v_mul_f32_e32 v89, v75, v42
	v_mul_f32_e32 v93, v71, v44
	v_mul_f32_e32 v82, v71, v46
	v_mul_f32_e32 v86, v76, v49
	v_mul_f32_e32 v90, v76, v48
	v_mul_f32_e32 v94, v72, v50
	v_mul_f32_e32 v83, v72, v52
	v_mul_f32_e32 v87, v77, v55
	v_mul_f32_e32 v91, v77, v54
	v_mul_f32_e32 v95, v73, v56
	v_mul_f32_e32 v84, v73, v58
	s_waitcnt lgkmcnt(1)
	v_mul_f32_e32 v88, v78, v61
	v_mul_f32_e32 v92, v78, v60
	s_waitcnt lgkmcnt(0)
	v_mul_f32_e32 v96, v74, v62
	v_cvt_pk_bf16_f32 v112, v81, v82
	v_cvt_pk_bf16_f32 v113, v83, v84
	v_cvt_pk_bf16_f32 v114, v85, v86
	v_cvt_pk_bf16_f32 v115, v87, v88
	v_cvt_pk_bf16_f32 v116, v89, v90
	v_cvt_pk_bf16_f32 v117, v91, v92
	v_cvt_pk_bf16_f32 v118, v93, v94
	v_cvt_pk_bf16_f32 v119, v95, v96
	v_cvt_pk_bf16_f32 v120, v45, v51
	v_cvt_pk_bf16_f32 v121, v57, v63
	ds_write_b16 v122, v112 offset:50880
	ds_write_b16_d16_hi v122, v112 offset:51024
	ds_write_b16 v122, v113 offset:51168
	ds_write_b16_d16_hi v122, v113 offset:51312
	ds_write_b16 v122, v114 offset:55488
	ds_write_b16_d16_hi v122, v114 offset:55632
	ds_write_b16 v122, v115 offset:55776
	ds_write_b16_d16_hi v122, v115 offset:55920
	ds_write_b16 v122, v116 offset:57792
	ds_write_b16_d16_hi v122, v116 offset:57936
	ds_write_b16 v122, v117 offset:58080
	ds_write_b16_d16_hi v122, v117 offset:58224
	ds_write_b16 v122, v118 offset:60096
	ds_write_b16_d16_hi v122, v118 offset:60240
	ds_write_b16 v122, v119 offset:60384
	ds_write_b16_d16_hi v122, v119 offset:60528
	ds_write_b64 v139, v[114:115] offset:24
	ds_write_b64 v139, v[116:117] offset:56
	ds_write_b64 v140, v[120:121] offset:56
	v_add_u32_e32 v123, 0x18d00, v143
	ds_write_b32 v123, v74
	s_setprio 0
	s_branch .Lpq1_end
